# final out stores use sc1 only (device-scope write-through) instead of sc0 sc1
# baseline (speedup 1.0000x reference)
;     __device__ __forceinline__ void fused(f32x4 (&acc)[2][2][4][2], const Unit& u, int wr, int wc, int fr, int fq, PG8_LAS unsigned char* lds, int wid, int lane) const {
;     ...
; #pragma unroll
;         for (int bj = 0; bj < 2; ++bj)
; #pragma unroll
;             for (int n = 0; n < 2; ++n) { const f32x4 w4 = *(const f32x4*)(fw + col0 + bj * HALF + n * 16);
; #pragma unroll
;                 for (int ai = 0; ai < 2; ++ai)
; #pragma unroll
;                     for (int m = 0; m < 4; ++m) { const int rl = ai * HALF + wr * 64 + m * 16 + fr; const float rs = Sr[rl];
;                         *(f32x4*)(out + (size_t)(u.pm * BM + rl) * 1024 + col0 + bj * HALF + n * 16) = acc[ai][bj][m][n] * rs * w4; } }
.LBB0_1122:
	s_or_b64 exec, exec, s[4:5]
	v_readlane_b32 s0, v239, 12
	v_lshlrev_b64 v[146:147], 2, v[130:131]
	v_readlane_b32 s14, v239, 26
	v_readlane_b32 s15, v239, 27
	s_waitcnt lgkmcnt(0)
	s_barrier
	v_readlane_b32 s1, v239, 13
	v_lshl_add_u64 v[130:131], s[14:15], 0, v[146:147]
	global_load_dwordx4 v[154:157], v[130:131], off
	v_readlane_b32 s2, v239, 14
	v_readlane_b32 s3, v239, 15
	v_readlane_b32 s0, v239, 1
	v_lshl_add_u32 v166, v148, 2, 0
	v_readlane_b32 s1, v239, 2
	v_add_u32_e32 v166, 0x1000, v166
	v_readlane_b32 s4, v239, 16
	v_lshl_add_u64 v[128:129], s[0:1], 0, v[128:129]
	v_lshl_add_u64 v[148:149], s[0:1], 0, v[132:133]
	v_lshl_add_u64 v[150:151], s[0:1], 0, v[134:135]
	v_lshl_add_u64 v[152:153], s[0:1], 0, v[136:137]
	v_lshl_add_u64 v[158:159], s[0:1], 0, v[138:139]
	v_lshl_add_u64 v[160:161], s[0:1], 0, v[140:141]
	v_lshl_add_u64 v[162:163], s[0:1], 0, v[142:143]
	v_lshl_add_u64 v[164:165], s[0:1], 0, v[144:145]
	v_lshl_add_u64 v[132:133], v[128:129], 0, v[146:147]
	v_lshl_add_u64 v[134:135], v[148:149], 0, v[146:147]
	v_lshl_add_u64 v[136:137], v[150:151], 0, v[146:147]
	v_lshl_add_u64 v[138:139], v[152:153], 0, v[146:147]
	v_lshl_add_u64 v[140:141], v[158:159], 0, v[146:147]
	v_lshl_add_u64 v[142:143], v[160:161], 0, v[146:147]
	v_lshl_add_u64 v[144:145], v[162:163], 0, v[146:147]
	ds_read2_b32 v[152:153], v166 offset1:16
	v_lshl_add_u64 v[128:129], v[164:165], 0, v[146:147]
	ds_read2_b32 v[150:151], v166 offset0:32 offset1:48
	ds_read2_b32 v[148:149], v166 offset0:128 offset1:144
	ds_read2_b32 v[146:147], v166 offset0:160 offset1:176
	v_readlane_b32 s5, v239, 17
	v_readlane_b32 s6, v239, 18
	s_waitcnt lgkmcnt(3)
	v_pk_mul_f32 v[158:159], v[124:125], v[152:153] op_sel_hi:[1,0]
	v_pk_mul_f32 v[126:127], v[126:127], v[152:153] op_sel_hi:[1,0]
	v_mov_b32_e32 v124, v153
	s_waitcnt lgkmcnt(2)
	v_pk_mul_f32 v[160:161], v[92:93], v[150:151] op_sel_hi:[1,0]
	v_mov_b32_e32 v92, v151
	s_waitcnt lgkmcnt(1)
	v_pk_mul_f32 v[162:163], v[60:61], v[148:149] op_sel_hi:[1,0]
	v_mov_b32_e32 v60, v149
	s_waitcnt lgkmcnt(0)
	v_pk_mul_f32 v[166:167], v[28:29], v[146:147] op_sel_hi:[1,0]
	v_mov_b32_e32 v28, v147
	v_pk_mul_f32 v[94:95], v[94:95], v[150:151] op_sel_hi:[1,0]
	v_pk_mul_f32 v[62:63], v[62:63], v[148:149] op_sel_hi:[1,0]
	v_pk_mul_f32 v[30:31], v[30:31], v[146:147] op_sel_hi:[1,0]
	v_pk_mul_f32 v[108:109], v[108:109], v[124:125] op_sel_hi:[1,0]
	v_pk_mul_f32 v[110:111], v[110:111], v[124:125] op_sel_hi:[1,0]
	v_pk_mul_f32 v[164:165], v[76:77], v[92:93] op_sel_hi:[1,0]
	v_pk_mul_f32 v[168:169], v[78:79], v[92:93] op_sel_hi:[1,0]
	v_pk_mul_f32 v[170:171], v[44:45], v[60:61] op_sel_hi:[1,0]
	v_pk_mul_f32 v[172:173], v[46:47], v[60:61] op_sel_hi:[1,0]
	v_pk_mul_f32 v[174:175], v[12:13], v[28:29] op_sel_hi:[1,0]
	v_pk_mul_f32 v[176:177], v[14:15], v[28:29] op_sel_hi:[1,0]
	v_pk_mul_f32 v[56:57], v[56:57], v[148:149] op_sel_hi:[1,0]
	v_pk_mul_f32 v[58:59], v[58:59], v[148:149] op_sel_hi:[1,0]
	v_pk_mul_f32 v[72:73], v[72:73], v[92:93] op_sel_hi:[1,0]
	v_pk_mul_f32 v[74:75], v[74:75], v[92:93] op_sel_hi:[1,0]
	v_pk_mul_f32 v[32:33], v[32:33], v[60:61] op_sel_hi:[1,0]
	v_pk_mul_f32 v[34:35], v[34:35], v[60:61] op_sel_hi:[1,0]
	v_readlane_b32 s7, v239, 19
	v_readlane_b32 s8, v239, 20
	v_readlane_b32 s9, v239, 21
	v_readlane_b32 s10, v239, 22
	v_readlane_b32 s11, v239, 23
	v_readlane_b32 s12, v239, 24
	v_readlane_b32 s13, v239, 25
	v_readlane_b32 s2, v239, 3
	v_readlane_b32 s3, v239, 4
	s_waitcnt vmcnt(0)
	v_pk_mul_f32 v[14:15], v[156:157], v[126:127]
	v_pk_mul_f32 v[12:13], v[154:155], v[158:159]
	v_pk_mul_f32 v[46:47], v[156:157], v[110:111]
	v_pk_mul_f32 v[44:45], v[154:155], v[108:109]
	v_pk_mul_f32 v[78:79], v[156:157], v[94:95]
	v_pk_mul_f32 v[76:77], v[154:155], v[160:161]
	v_pk_mul_f32 v[110:111], v[156:157], v[168:169]
	v_pk_mul_f32 v[108:109], v[154:155], v[164:165]
	v_pk_mul_f32 v[160:161], v[156:157], v[62:63]
	v_pk_mul_f32 v[158:159], v[154:155], v[162:163]
	v_pk_mul_f32 v[164:165], v[156:157], v[172:173]
	v_pk_mul_f32 v[162:163], v[154:155], v[170:171]
	v_pk_mul_f32 v[168:169], v[156:157], v[30:31]
	v_pk_mul_f32 v[166:167], v[154:155], v[166:167]
	v_pk_mul_f32 v[156:157], v[156:157], v[176:177]
	v_pk_mul_f32 v[154:155], v[154:155], v[174:175]
	global_store_dwordx4 v[132:133], v[12:15], off sc1
	global_store_dwordx4 v[134:135], v[44:47], off sc1
	global_store_dwordx4 v[136:137], v[76:79], off sc1
	global_store_dwordx4 v[138:139], v[108:111], off sc1
	global_store_dwordx4 v[140:141], v[158:161], off sc1
	global_store_dwordx4 v[142:143], v[162:165], off sc1
	global_store_dwordx4 v[144:145], v[166:169], off sc1
	global_store_dwordx4 v[128:129], v[154:157], off sc1
	global_load_dwordx4 v[12:15], v[130:131], off offset:64
	v_pk_mul_f32 v[30:31], v[120:121], v[152:153] op_sel_hi:[1,0]
	v_pk_mul_f32 v[44:45], v[122:123], v[152:153] op_sel_hi:[1,0]
	v_pk_mul_f32 v[46:47], v[88:89], v[150:151] op_sel_hi:[1,0]
	v_pk_mul_f32 v[62:63], v[90:91], v[150:151] op_sel_hi:[1,0]
	v_pk_mul_f32 v[76:77], v[24:25], v[146:147] op_sel_hi:[1,0]
	v_pk_mul_f32 v[78:79], v[26:27], v[146:147] op_sel_hi:[1,0]
	v_pk_mul_f32 v[24:25], v[104:105], v[124:125] op_sel_hi:[1,0]
	v_pk_mul_f32 v[26:27], v[106:107], v[124:125] op_sel_hi:[1,0]
	v_pk_mul_f32 v[88:89], v[40:41], v[60:61] op_sel_hi:[1,0]
	v_pk_mul_f32 v[90:91], v[42:43], v[60:61] op_sel_hi:[1,0]
	v_pk_mul_f32 v[94:95], v[8:9], v[28:29] op_sel_hi:[1,0]
	v_pk_mul_f32 v[104:105], v[10:11], v[28:29] op_sel_hi:[1,0]
	s_waitcnt vmcnt(0)
;     __device__ __forceinline__ void fused(f32x4 (&acc)[2][2][4][2], const Unit& u, int wr, int wc, int fr, int fq, PG8_LAS unsigned char* lds, int wid, int lane) const {
;     ...
; #pragma unroll
;         for (int bj = 0; bj < 2; ++bj)
; #pragma unroll
;             for (int n = 0; n < 2; ++n) { const f32x4 w4 = *(const f32x4*)(fw + col0 + bj * HALF + n * 16);
; #pragma unroll
;                 for (int ai = 0; ai < 2; ++ai)
; #pragma unroll
;                     for (int m = 0; m < 4; ++m) { const int rl = ai * HALF + wr * 64 + m * 16 + fr; const float rs = Sr[rl];
;                         *(f32x4*)(out + (size_t)(u.pm * BM + rl) * 1024 + col0 + bj * HALF + n * 16) = acc[ai][bj][m][n] * rs * w4; } }
	v_pk_mul_f32 v[10:11], v[14:15], v[44:45]
	v_pk_mul_f32 v[8:9], v[12:13], v[30:31]
	v_pk_mul_f32 v[26:27], v[14:15], v[26:27]
	v_pk_mul_f32 v[24:25], v[12:13], v[24:25]
	v_pk_mul_f32 v[42:43], v[14:15], v[62:63]
	v_pk_mul_f32 v[40:41], v[12:13], v[46:47]
	v_pk_mul_f32 v[46:47], v[14:15], v[74:75]
	v_pk_mul_f32 v[44:45], v[12:13], v[72:73]
	v_pk_mul_f32 v[58:59], v[14:15], v[58:59]
	v_pk_mul_f32 v[56:57], v[12:13], v[56:57]
	v_pk_mul_f32 v[74:75], v[14:15], v[90:91]
	v_pk_mul_f32 v[72:73], v[12:13], v[88:89]
	v_pk_mul_f32 v[78:79], v[14:15], v[78:79]
	v_pk_mul_f32 v[76:77], v[12:13], v[76:77]
	v_pk_mul_f32 v[14:15], v[14:15], v[104:105]
	v_pk_mul_f32 v[12:13], v[12:13], v[94:95]
	global_store_dwordx4 v[132:133], v[8:11], off offset:64 sc1
	global_store_dwordx4 v[134:135], v[24:27], off offset:64 sc1
	global_store_dwordx4 v[136:137], v[40:43], off offset:64 sc1
	global_store_dwordx4 v[138:139], v[44:47], off offset:64 sc1
	global_store_dwordx4 v[140:141], v[56:59], off offset:64 sc1
	global_store_dwordx4 v[142:143], v[72:75], off offset:64 sc1
	global_store_dwordx4 v[144:145], v[76:79], off offset:64 sc1
	global_store_dwordx4 v[128:129], v[12:15], off offset:64 sc1
	global_load_dwordx4 v[8:11], v[130:131], off offset:512
	v_pk_mul_f32 v[24:25], v[84:85], v[150:151] op_sel_hi:[1,0]
	v_pk_mul_f32 v[12:13], v[116:117], v[152:153] op_sel_hi:[1,0]
	v_pk_mul_f32 v[14:15], v[118:119], v[152:153] op_sel_hi:[1,0]
	v_pk_mul_f32 v[26:27], v[86:87], v[150:151] op_sel_hi:[1,0]
	v_pk_mul_f32 v[30:31], v[52:53], v[148:149] op_sel_hi:[1,0]
	v_pk_mul_f32 v[40:41], v[54:55], v[148:149] op_sel_hi:[1,0]
	v_pk_mul_f32 v[44:45], v[20:21], v[146:147] op_sel_hi:[1,0]
	v_pk_mul_f32 v[46:47], v[22:23], v[146:147] op_sel_hi:[1,0]
	v_pk_mul_f32 v[20:21], v[100:101], v[124:125] op_sel_hi:[1,0]
	v_pk_mul_f32 v[22:23], v[102:103], v[124:125] op_sel_hi:[1,0]
	v_pk_mul_f32 v[42:43], v[68:69], v[92:93] op_sel_hi:[1,0]
	v_pk_mul_f32 v[52:53], v[70:71], v[92:93] op_sel_hi:[1,0]
	v_pk_mul_f32 v[54:55], v[36:37], v[60:61] op_sel_hi:[1,0]
	v_pk_mul_f32 v[56:57], v[38:39], v[60:61] op_sel_hi:[1,0]
	v_pk_mul_f32 v[58:59], v[4:5], v[28:29] op_sel_hi:[1,0]
	v_pk_mul_f32 v[62:63], v[6:7], v[28:29] op_sel_hi:[1,0]
	s_waitcnt vmcnt(0)
	v_pk_mul_f32 v[6:7], v[14:15], v[10:11]
	v_pk_mul_f32 v[4:5], v[12:13], v[8:9]
	v_pk_mul_f32 v[14:15], v[22:23], v[10:11]
	v_pk_mul_f32 v[12:13], v[20:21], v[8:9]
	v_pk_mul_f32 v[22:23], v[26:27], v[10:11]
	v_pk_mul_f32 v[20:21], v[24:25], v[8:9]
	v_pk_mul_f32 v[26:27], v[52:53], v[10:11]
	v_pk_mul_f32 v[24:25], v[42:43], v[8:9]
	v_pk_mul_f32 v[38:39], v[40:41], v[10:11]
	v_pk_mul_f32 v[36:37], v[30:31], v[8:9]
	v_pk_mul_f32 v[42:43], v[56:57], v[10:11]
	v_pk_mul_f32 v[40:41], v[54:55], v[8:9]
	v_pk_mul_f32 v[46:47], v[46:47], v[10:11]
	v_pk_mul_f32 v[44:45], v[44:45], v[8:9]
	v_pk_mul_f32 v[10:11], v[10:11], v[62:63]
	v_pk_mul_f32 v[8:9], v[8:9], v[58:59]
	global_store_dwordx4 v[132:133], v[4:7], off offset:512 sc1
	global_store_dwordx4 v[134:135], v[12:15], off offset:512 sc1
	global_store_dwordx4 v[136:137], v[20:23], off offset:512 sc1
	global_store_dwordx4 v[138:139], v[24:27], off offset:512 sc1
	global_store_dwordx4 v[140:141], v[36:39], off offset:512 sc1
	global_store_dwordx4 v[142:143], v[40:43], off offset:512 sc1
	global_store_dwordx4 v[144:145], v[44:47], off offset:512 sc1
	global_store_dwordx4 v[128:129], v[8:11], off offset:512 sc1
	global_load_dwordx4 v[4:7], v[130:131], off offset:576
	v_pk_mul_f32 v[12:13], v[80:81], v[150:151] op_sel_hi:[1,0]
	v_pk_mul_f32 v[8:9], v[112:113], v[152:153] op_sel_hi:[1,0]
	v_pk_mul_f32 v[10:11], v[114:115], v[152:153] op_sel_hi:[1,0]
	v_pk_mul_f32 v[14:15], v[82:83], v[150:151] op_sel_hi:[1,0]
	v_pk_mul_f32 v[20:21], v[48:49], v[148:149] op_sel_hi:[1,0]
	v_pk_mul_f32 v[22:23], v[50:51], v[148:149] op_sel_hi:[1,0]
	v_pk_mul_f32 v[36:37], v[16:17], v[146:147] op_sel_hi:[1,0]
	v_pk_mul_f32 v[30:31], v[18:19], v[146:147] op_sel_hi:[1,0]
	v_pk_mul_f32 v[16:17], v[96:97], v[124:125] op_sel_hi:[1,0]
	v_pk_mul_f32 v[18:19], v[98:99], v[124:125] op_sel_hi:[1,0]
	v_pk_mul_f32 v[24:25], v[64:65], v[92:93] op_sel_hi:[1,0]
	v_pk_mul_f32 v[26:27], v[66:67], v[92:93] op_sel_hi:[1,0]
	v_pk_mul_f32 v[38:39], v[0:1], v[28:29] op_sel_hi:[1,0]
	v_pk_mul_f32 v[40:41], v[2:3], v[28:29] op_sel_hi:[1,0]
	s_waitcnt vmcnt(0)
	v_pk_mul_f32 v[2:3], v[10:11], v[6:7]
	v_pk_mul_f32 v[0:1], v[8:9], v[4:5]
	v_pk_mul_f32 v[10:11], v[18:19], v[6:7]
	v_pk_mul_f32 v[8:9], v[16:17], v[4:5]
	v_pk_mul_f32 v[14:15], v[14:15], v[6:7]
	v_pk_mul_f32 v[12:13], v[12:13], v[4:5]
	v_pk_mul_f32 v[18:19], v[26:27], v[6:7]
	v_pk_mul_f32 v[16:17], v[24:25], v[4:5]
	v_pk_mul_f32 v[22:23], v[22:23], v[6:7]
	v_pk_mul_f32 v[20:21], v[20:21], v[4:5]
	v_pk_mul_f32 v[26:27], v[34:35], v[6:7]
	v_pk_mul_f32 v[24:25], v[32:33], v[4:5]
	v_pk_mul_f32 v[30:31], v[30:31], v[6:7]
	v_pk_mul_f32 v[28:29], v[36:37], v[4:5]
	v_pk_mul_f32 v[6:7], v[40:41], v[6:7]
	v_pk_mul_f32 v[4:5], v[38:39], v[4:5]
	global_store_dwordx4 v[132:133], v[0:3], off offset:576 sc1
	global_store_dwordx4 v[134:135], v[8:11], off offset:576 sc1
	global_store_dwordx4 v[136:137], v[12:15], off offset:576 sc1
	global_store_dwordx4 v[138:139], v[16:19], off offset:576 sc1
	global_store_dwordx4 v[140:141], v[20:23], off offset:576 sc1
	global_store_dwordx4 v[142:143], v[24:27], off offset:576 sc1
	global_store_dwordx4 v[144:145], v[28:31], off offset:576 sc1
	global_store_dwordx4 v[128:129], v[4:7], off offset:576 sc1
	s_endpgm
